# attention work queue: the 128 deferred QKV-gate GEMM units are dealt after the 96 longest MoBA units instead of after 192 (LPT-style ordering); otherwise the merged-wait version
# speedup vs baseline: 1.0156x; 1.0156x over previous
; __device__ __forceinline__ void wg_unit_B(const bf16_t* qkv, const float* kmean, bf16_t* outB, int b, int hb, int qb, LAS unsigned char* lds, int wid, const WaveCtx& c, int tid) {
;     const int own = qb, qt = 8 * qb + wid, qp = 32 * qt + c.q, head = 12 + hb;
;     const bf16_t* rowb = qkv + (size_t)b * SEQ * LDQ;
;     bf16x8 qf[4]; load_q(qf, rowb + (size_t)qp * LDQ + head * 64, c.h);
;     const bf16_t* kbase = rowb + MIXW + head * 64; const bf16_t* vbase = rowb + 2 * MIXW + head * 64;
;     float gate[7];
; #pragma unroll
;     for (int n = 0; n < 7; ++n) {
;         gate[n] = -INFINITY;
;         if (n < own) {
;             const float* km = kmean + (size_t)((b * 6 + hb) * 8 + n) * 64 + 8 * c.h;
;             float a = 0.f;
; #pragma unroll
;             for (int ks = 0; ks < 4; ++ks) {
;                 const f32x4 k0 = *(const f32x4*)(km + 16 * ks), k1 = *(const f32x4*)(km + 16 * ks + 4);
; #pragma unroll
;                 for (int j = 0; j < 4; ++j) { a += bf2f((unsigned short)qf[ks][j]) * k0[j]; a += bf2f((unsigned short)qf[ks][4 + j]) * k1[j]; }
;             }
;             a = xor32_sum(a);
;             gate[n] = a;
;         }
; __device__ __forceinline__ void attn_phase(const Params& p, unsigned char* ws, int layer, LAS unsigned char* lds, const int tid, int rep) {
;     ...
;             const unsigned u = (unsigned)__builtin_amdgcn_readfirstlane((int)*qw);
;             const unsigned ngu = (gridDim.x == 256) ? 128u : 0u;
;             if (u >= 384u + ngu) break;
;             if (u >= 192u && u < 192u + ngu) {
;                 pg8::StaticOrder so; so.init(M, NQKVG, 256, (int)(u - 192u));
;                 OneUnit S1; so.next(7, S1.u0);
;                 pg8::Gemm g{(const bf16_t*)(ws + WS_H), (const bf16_t*)(ws + WS_W + W_QKVG), M, NQKVG, DM};
;                 EpiQKVG E{(bf16_t*)(ws + WS_QKV), (bf16_t*)(ws + WS_GATES), p.b_gate + (size_t)layer * NG, (const float*)(ws + WS_COS), (const float*)(ws + WS_SIN), (float*)(ws + WS_KMEAN)};
;                 pg8::gemm_phase<EpiQKVG, OneUnit, false, GSP2>(lds, g, S1, E, t2);
;                 if (wid >= 4) __builtin_amdgcn_s_setprio(1);
;                 continue;
;             }
;             const unsigned ub = (u < 192u) ? u : u - ngu;
;             const int qb = 7 - (int)(ub / 48u), r2 = (int)(ub % 48u);
;             wg_unit_B(qkv, kmean, outB, r2 / 6, r2 % 6, qb, lds, wid, c, t2);
.LBB0_445:
	s_or_b64 exec, exec, s[2:3]
	v_mov_b32_e32 v0, s41
	s_waitcnt lgkmcnt(0)
	s_barrier
	ds_read_b32 v0, v0
	s_mov_b64 s[2:3], -1
	s_waitcnt lgkmcnt(0)
	v_readfirstlane_b32 s90, v0
	s_cmp_ge_u32 s90, s45
	s_cbranch_scc1 .LBB0_442
	s_sub_i32 s4, s90, 96
	s_cmp_lt_u32 s4, s46
	s_cselect_b64 s[2:3], -1, 0
	s_cselect_b32 s90, s4, s90
	s_cselect_b32 s5, 0xc0, 0
	s_add_i32 s90, s90, s5
	s_andn2_b64 vcc, exec, s[2:3]
	s_mov_b64 s[2:3], -1
	s_cbranch_vccz .LBB0_507
	s_add_i32 s4, s46, 96
	s_cmp_ge_u32 s90, s4
	s_cselect_b32 s2, s46, 0
	s_sub_i32 s2, s90, s2
	s_mul_hi_u32 s3, s2, 0xaaaaaaab
	s_lshr_b32 s3, s3, 5
	s_sub_i32 s59, 7, s3
	s_mul_i32 s3, s3, 48
	s_sub_i32 s3, s2, s3
	s_and_b32 s4, s3, 0xff
	s_mulk_i32 s4, 0xab
	s_lshr_b32 s91, s4, 10
	s_mul_i32 s6, s91, 6
	s_sub_i32 s3, s3, s6
	s_lshl_b32 s20, s59, 8
	s_and_b32 s21, s3, 0xff
	s_add_i32 s20, s20, s34
	s_mul_i32 s3, s91, 0x1200000
	s_add_u32 s16, s84, s3
	v_and_b32_e32 v10, 31, v150
	s_addc_u32 s17, s85, 0
	v_or_b32_e32 v151, s20, v10
	v_mov_b64_e32 v[0:1], s[16:17]
	v_bfe_u32 v11, v150, 5, 1
	v_mad_i64_i32 v[0:1], s[4:5], v151, s71, v[0:1]
	s_lshl_b32 s80, s21, 7
	v_lshl_add_u64 v[0:1], v[0:1], 0, s[80:81]
	v_lshlrev_b32_e32 v4, 4, v11
	v_mov_b32_e32 v5, v65
	v_lshl_add_u64 v[0:1], v[0:1], 0, v[4:5]
	flat_load_dwordx4 v[114:117], v[0:1] offset:1536
	flat_load_dwordx4 v[118:121], v[0:1] offset:1568
	flat_load_dwordx4 v[122:125], v[0:1] offset:1600
	flat_load_dwordx4 v[126:129], v[0:1] offset:1632
	s_add_i32 s6, s6, s21
	s_lshl_b32 s3, s6, 9
	v_lshlrev_b32_e32 v64, 5, v11
	s_cmpk_lt_u32 s2, 0x150
	v_lshl_add_u64 v[6:7], s[48:49], 0, v[64:65]
	v_mov_b32_e32 v5, 0xff800000
	s_cselect_b64 s[4:5], -1, 0
	s_cmpk_gt_u32 s2, 0x14f
	v_mov_b32_e32 v12, 0xff800000
	s_cbranch_scc1 .LBB0_449
	s_lshl_b32 s80, s3, 2
	v_lshl_add_u64 v[8:9], v[6:7], 0, s[80:81]
	global_load_dwordx4 v[24:27], v[8:9], off
	global_load_dwordx4 v[28:31], v[8:9], off offset:16
	global_load_dwordx4 v[32:35], v[8:9], off offset:64
	global_load_dwordx4 v[36:39], v[8:9], off offset:80
	global_load_dwordx4 v[40:43], v[8:9], off offset:128
	global_load_dwordx4 v[44:47], v[8:9], off offset:144
	global_load_dwordx4 v[130:133], v[8:9], off offset:192
	global_load_dwordx4 v[134:137], v[8:9], off offset:208
	s_waitcnt vmcnt(6) lgkmcnt(0)
	v_lshlrev_b32_e32 v16, 16, v114
	v_fma_f32 v18, v24, v16, 0
	v_lshlrev_b32_e32 v0, 16, v116
	v_fmac_f32_e32 v18, v28, v0
	v_and_b32_e32 v0, 0xffff0000, v114
	v_fmac_f32_e32 v18, v25, v0
	v_and_b32_e32 v0, 0xffff0000, v116
	v_fmac_f32_e32 v18, v29, v0
	v_lshlrev_b32_e32 v0, 16, v115
	v_fmac_f32_e32 v18, v26, v0
	v_lshlrev_b32_e32 v0, 16, v117
	v_fmac_f32_e32 v18, v30, v0
	v_and_b32_e32 v0, 0xffff0000, v115
	v_fmac_f32_e32 v18, v27, v0
	v_and_b32_e32 v0, 0xffff0000, v117
	v_fmac_f32_e32 v18, v31, v0
	v_lshlrev_b32_e32 v16, 16, v118
	s_waitcnt vmcnt(4)
	v_fmac_f32_e32 v18, v32, v16
	v_lshlrev_b32_e32 v0, 16, v120
	v_fmac_f32_e32 v18, v36, v0
	v_and_b32_e32 v0, 0xffff0000, v118
	v_fmac_f32_e32 v18, v33, v0
	v_and_b32_e32 v0, 0xffff0000, v120
	v_fmac_f32_e32 v18, v37, v0
	v_lshlrev_b32_e32 v0, 16, v119
	v_fmac_f32_e32 v18, v34, v0
	v_lshlrev_b32_e32 v0, 16, v121
	v_fmac_f32_e32 v18, v38, v0
	v_and_b32_e32 v0, 0xffff0000, v119
	v_fmac_f32_e32 v18, v35, v0
	v_and_b32_e32 v0, 0xffff0000, v121
	v_fmac_f32_e32 v18, v39, v0
	v_lshlrev_b32_e32 v16, 16, v122
	s_waitcnt vmcnt(2)
	v_fmac_f32_e32 v18, v40, v16
	v_lshlrev_b32_e32 v0, 16, v124
	v_fmac_f32_e32 v18, v44, v0
	v_and_b32_e32 v0, 0xffff0000, v122
	v_fmac_f32_e32 v18, v41, v0
	v_and_b32_e32 v0, 0xffff0000, v124
	v_fmac_f32_e32 v18, v45, v0
	v_lshlrev_b32_e32 v0, 16, v123
	v_fmac_f32_e32 v18, v42, v0
	v_lshlrev_b32_e32 v0, 16, v125
	v_fmac_f32_e32 v18, v46, v0
	v_and_b32_e32 v0, 0xffff0000, v123
	v_fmac_f32_e32 v18, v43, v0
	v_and_b32_e32 v0, 0xffff0000, v125
	v_fmac_f32_e32 v18, v47, v0
	v_lshlrev_b32_e32 v9, 16, v126
	v_lshlrev_b32_e32 v8, 16, v128
	s_waitcnt vmcnt(0)
	v_mov_b32_e32 v0, v130
	v_mov_b32_e32 v1, v131
	v_mov_b32_e32 v2, v132
	v_mov_b32_e32 v3, v133
	v_mov_b32_e32 v12, v134
	v_mov_b32_e32 v13, v135
	v_mov_b32_e32 v14, v136
	v_mov_b32_e32 v15, v137
	v_mov_b32_e32 v17, v0
	v_mov_b32_e32 v16, v12
	v_pk_mul_f32 v[8:9], v[16:17], v[8:9]
	s_nop 0
	v_add_f32_e32 v0, v9, v18
	v_add_f32_e32 v12, v8, v0
	v_and_b32_e32 v9, 0xffff0000, v126
	v_and_b32_e32 v8, 0xffff0000, v128
	v_mov_b32_e32 v0, v13
	v_pk_mul_f32 v[0:1], v[0:1], v[8:9]
	v_mov_b32_e32 v8, v14
	v_add_f32_e32 v1, v1, v12
	v_add_f32_e32 v12, v0, v1
	v_lshlrev_b32_e32 v1, 16, v127
	v_lshlrev_b32_e32 v0, 16, v129
	v_mov_b32_e32 v9, v2
	v_pk_mul_f32 v[0:1], v[8:9], v[0:1]
	v_mov_b32_e32 v2, v15
	v_add_f32_e32 v1, v1, v12
	v_add_f32_e32 v8, v0, v1
	v_and_b32_e32 v1, 0xffff0000, v127
	v_and_b32_e32 v0, 0xffff0000, v129
	v_pk_mul_f32 v[0:1], v[2:3], v[0:1]
	s_nop 0
	v_add_f32_e32 v1, v1, v8
	v_add_f32_e32 v0, v0, v1
	v_mov_b32_e32 v1, v0
	s_nop 1
	v_permlane32_swap_b32_e32 v0, v1
	v_add_f32_e32 v12, v0, v1
